# non-temporal loads for the once-read f32 ada and conversion weights
# speedup vs baseline: 1.0850x; 1.0032x over previous
.LBB0_30:
	s_cmpk_gt_u32 s62, 0x277
	s_cbranch_scc0 .LBB0_59
	s_cmpk_gt_u32 s62, 0x337
	s_cbranch_scc0 .LBB0_45
	v_mov_b32_e32 v0, v184
	s_add_i32 s28, s63, 0xfffff990
	v_ashrrev_i32_e32 v0, 8, v0
	v_add_u32_e32 v0, s28, v0
	v_ashrrev_i32_e32 v1, 31, v0
	v_lshrrev_b32_e32 v1, 28, v1
	v_add_u32_e32 v1, v0, v1
	v_ashrrev_i32_e32 v6, 4, v1
	v_and_b32_e32 v1, 0xfff0, v1
	v_ashrrev_i32_e32 v7, 31, v6
	v_sub_u32_e32 v4, v0, v1
	v_lshlrev_b64 v[0:1], 18, v[6:7]
	v_lshl_add_u64 v[2:3], s[16:17], 0, v[0:1]
	v_lshrrev_b16_sdwa v0, v53, sext(v4) dst_sel:DWORD dst_unused:UNUSED_PAD src0_sel:DWORD src1_sel:BYTE_0
	v_and_b32_e32 v0, 3, v0
	v_add_u16_e32 v0, v4, v0
	v_ashrrev_i16_sdwa v5, v62, sext(v0) dst_sel:DWORD dst_unused:UNUSED_PAD src0_sel:DWORD src1_sel:BYTE_0
	v_and_b32_e32 v0, 0xfc, v0
	v_mov_b32_e32 v1, v184
	v_mov_b32_e32 v9, v184
	v_sub_u16_e32 v0, v4, v0
	v_lshlrev_b32_sdwa v12, v63, sext(v0) dst_sel:DWORD dst_unused:UNUSED_PAD src0_sel:DWORD src1_sel:BYTE_0
	v_lshlrev_b32_e32 v4, 2, v9
	v_and_b32_e32 v15, 60, v4
	v_or_b32_e32 v4, v12, v15
	v_lshlrev_b32_sdwa v8, v63, sext(v5) dst_sel:DWORD dst_unused:UNUSED_PAD src0_sel:DWORD src1_sel:WORD_0
	v_ashrrev_i32_e32 v5, 31, v4
	v_bfe_u32 v13, v9, 4, 4
	v_cmp_gt_i32_e32 vcc, s30, v4
	v_lshl_add_u64 v[10:11], v[4:5], 2, v[2:3]
	v_mov_b32_e32 v0, 0
	v_mov_b32_e32 v2, 0
	v_mov_b32_e32 v3, 0
	v_mov_b32_e32 v4, 0
	v_mov_b32_e32 v5, 0
	s_barrier
	s_and_saveexec_b64 s[28:29], vcc
	s_cbranch_execz .LBB0_34
	v_or_b32_e32 v2, v8, v13
	v_ashrrev_i32_e32 v3, 31, v2
	v_lshlrev_b64 v[2:3], 10, v[2:3]
	v_lshl_add_u64 v[2:3], v[10:11], 0, v[2:3]
	global_load_dwordx4 v[2:5], v[2:3], off nt
.LBB0_34:
	s_or_b64 exec, exec, s[28:29]
	v_lshlrev_b32_e32 v1, 6, v1
	v_and_b32_e32 v14, 0xffffc000, v1
	v_mul_u32_u24_e32 v1, 0x90, v15
	v_or_b32_e32 v1, v14, v1
	s_waitcnt vmcnt(0)
	v_bfe_u32 v15, v2, 16, 1
	v_add3_u32 v2, v2, v15, s34
	v_lshl_add_u32 v15, v13, 1, v1
	v_bfe_u32 v1, v3, 16, 1
	v_add3_u32 v1, v3, v1, s34
	ds_write_b16_d16_hi v15, v1 offset:144
	v_bfe_u32 v1, v4, 16, 1
	v_add3_u32 v1, v4, v1, s34
	ds_write_b16_d16_hi v15, v1 offset:288
	v_bfe_u32 v1, v5, 16, 1
	v_add3_u32 v1, v5, v1, s34
	ds_write_b16_d16_hi v15, v2
	ds_write_b16_d16_hi v15, v1 offset:432
	v_mov_b32_e32 v1, 0
	v_mov_b32_e32 v2, 0
	v_mov_b32_e32 v3, 0
	s_and_saveexec_b64 s[28:29], vcc
	s_cbranch_execz .LBB0_36
	v_or3_b32 v0, v13, v8, 16
	v_ashrrev_i32_e32 v1, 31, v0
	v_lshlrev_b64 v[0:1], 10, v[0:1]
	v_lshl_add_u64 v[0:1], v[10:11], 0, v[0:1]
	global_load_dwordx4 v[0:3], v[0:1], off nt
.LBB0_36:
	s_or_b64 exec, exec, s[28:29]
	s_waitcnt vmcnt(0)
	v_bfe_u32 v4, v0, 16, 1
	v_add3_u32 v0, v0, v4, s34
	ds_write_b16_d16_hi v15, v0 offset:32
	v_bfe_u32 v0, v1, 16, 1
	v_add3_u32 v0, v1, v0, s34
	ds_write_b16_d16_hi v15, v0 offset:176
	v_bfe_u32 v0, v2, 16, 1
	v_add3_u32 v0, v2, v0, s34
	ds_write_b16_d16_hi v15, v0 offset:320
	v_bfe_u32 v0, v3, 16, 1
	v_add3_u32 v0, v3, v0, s34
	ds_write_b16_d16_hi v15, v0 offset:464
	v_mov_b32_e32 v0, 0
	v_mov_b32_e32 v2, 0
	v_mov_b32_e32 v3, 0
	v_mov_b32_e32 v4, 0
	v_mov_b32_e32 v5, 0
	s_and_saveexec_b64 s[28:29], vcc
	s_cbranch_execz .LBB0_38
	v_or3_b32 v2, v13, v8, 32
	v_ashrrev_i32_e32 v3, 31, v2
	v_lshlrev_b64 v[2:3], 10, v[2:3]
	v_lshl_add_u64 v[2:3], v[10:11], 0, v[2:3]
	global_load_dwordx4 v[2:5], v[2:3], off nt
.LBB0_38:
	s_or_b64 exec, exec, s[28:29]
	s_waitcnt vmcnt(0)
	v_bfe_u32 v1, v2, 16, 1
	v_add3_u32 v1, v2, v1, s34
	ds_write_b16_d16_hi v15, v1 offset:64
	v_bfe_u32 v1, v3, 16, 1
	v_add3_u32 v1, v3, v1, s34
	ds_write_b16_d16_hi v15, v1 offset:208
	v_bfe_u32 v1, v4, 16, 1
	v_add3_u32 v1, v4, v1, s34
	ds_write_b16_d16_hi v15, v1 offset:352
	v_bfe_u32 v1, v5, 16, 1
	v_add3_u32 v1, v5, v1, s34
	ds_write_b16_d16_hi v15, v1 offset:496
	v_mov_b32_e32 v1, 0
	v_mov_b32_e32 v2, 0
	v_mov_b32_e32 v3, 0
	s_and_saveexec_b64 s[28:29], vcc
	s_cbranch_execz .LBB0_40
	v_or3_b32 v0, v13, v8, 48
	v_ashrrev_i32_e32 v1, 31, v0
	v_lshlrev_b64 v[0:1], 10, v[0:1]
	v_lshl_add_u64 v[0:1], v[10:11], 0, v[0:1]
	global_load_dwordx4 v[0:3], v[0:1], off nt

.LBB0_45:
	s_and_b64 vcc, exec, s[28:29]
	s_cbranch_vccz .LBB0_81
	v_mov_b32_e32 v0, v184
	s_add_i32 s28, s63, 0xfffffb10
	v_ashrrev_i32_e32 v0, 8, v0
	v_add_u32_e32 v0, s28, v0
	v_ashrrev_i32_e32 v1, 31, v0
	v_lshrrev_b32_e32 v1, 28, v1
	v_add_u32_e32 v3, v0, v1
	v_and_b32_e32 v1, 0x3fffff0, v3
	v_sub_u32_e32 v0, v0, v1
	v_mov_b32_e32 v1, v184
	v_mov_b32_e32 v7, v184
	v_lshlrev_b32_e32 v10, 6, v0
	v_lshlrev_b32_e32 v2, 2, v7
	v_and_b32_e32 v13, 60, v2
	v_or_b32_e32 v2, v13, v10
	v_lshlrev_b32_e32 v0, 2, v3
	v_ashrrev_i32_e32 v3, 31, v2
	v_bfe_u32 v11, v7, 4, 4
	v_cmp_gt_i32_e32 vcc, s35, v2
	v_and_b32_e32 v6, 0xffffffc0, v0
	v_lshl_add_u64 v[8:9], v[2:3], 2, s[10:11]
	v_mov_b32_e32 v0, 0
	v_mov_b32_e32 v2, 0
	v_mov_b32_e32 v3, 0
	v_mov_b32_e32 v4, 0
	v_mov_b32_e32 v5, 0
	s_barrier
	s_and_saveexec_b64 s[28:29], vcc
	s_cbranch_execz .LBB0_48
	v_or_b32_e32 v2, v11, v6
	v_ashrrev_i32_e32 v3, 31, v2
	v_lshlrev_b64 v[2:3], 12, v[2:3]
	v_lshl_add_u64 v[2:3], v[8:9], 0, v[2:3]
	global_load_dwordx4 v[2:5], v[2:3], off nt
.LBB0_48:
	s_or_b64 exec, exec, s[28:29]
	v_lshlrev_b32_e32 v1, 6, v1
	v_and_b32_e32 v12, 0xffffc000, v1
	v_mul_u32_u24_e32 v1, 0x90, v13
	v_or_b32_e32 v1, v12, v1
	s_waitcnt vmcnt(0)
	v_bfe_u32 v13, v2, 16, 1
	v_add3_u32 v2, v2, v13, s34
	v_lshl_add_u32 v13, v11, 1, v1
	v_bfe_u32 v1, v3, 16, 1
	v_add3_u32 v1, v3, v1, s34
	ds_write_b16_d16_hi v13, v1 offset:144
	v_bfe_u32 v1, v4, 16, 1
	v_add3_u32 v1, v4, v1, s34
	ds_write_b16_d16_hi v13, v1 offset:288
	v_bfe_u32 v1, v5, 16, 1
	v_add3_u32 v1, v5, v1, s34
	ds_write_b16_d16_hi v13, v2
	ds_write_b16_d16_hi v13, v1 offset:432
	v_mov_b32_e32 v1, 0
	v_mov_b32_e32 v2, 0
	v_mov_b32_e32 v3, 0
	s_and_saveexec_b64 s[28:29], vcc
	s_cbranch_execz .LBB0_50
	v_or3_b32 v0, v11, v6, 16
	v_ashrrev_i32_e32 v1, 31, v0
	v_lshlrev_b64 v[0:1], 12, v[0:1]
	v_lshl_add_u64 v[0:1], v[8:9], 0, v[0:1]
	global_load_dwordx4 v[0:3], v[0:1], off nt
.LBB0_50:
	s_or_b64 exec, exec, s[28:29]
	s_waitcnt vmcnt(0)
	v_bfe_u32 v4, v0, 16, 1
	v_add3_u32 v0, v0, v4, s34
	ds_write_b16_d16_hi v13, v0 offset:32
	v_bfe_u32 v0, v1, 16, 1
	v_add3_u32 v0, v1, v0, s34
	ds_write_b16_d16_hi v13, v0 offset:176
	v_bfe_u32 v0, v2, 16, 1
	v_add3_u32 v0, v2, v0, s34
	ds_write_b16_d16_hi v13, v0 offset:320
	v_bfe_u32 v0, v3, 16, 1
	v_add3_u32 v0, v3, v0, s34
	ds_write_b16_d16_hi v13, v0 offset:464
	v_mov_b32_e32 v0, 0
	v_mov_b32_e32 v2, 0
	v_mov_b32_e32 v3, 0
	v_mov_b32_e32 v4, 0
	v_mov_b32_e32 v5, 0
	s_and_saveexec_b64 s[28:29], vcc
	s_cbranch_execz .LBB0_52
	v_or3_b32 v2, v11, v6, 32
	v_ashrrev_i32_e32 v3, 31, v2
	v_lshlrev_b64 v[2:3], 12, v[2:3]
	v_lshl_add_u64 v[2:3], v[8:9], 0, v[2:3]
	global_load_dwordx4 v[2:5], v[2:3], off nt
.LBB0_52:
	s_or_b64 exec, exec, s[28:29]
	s_waitcnt vmcnt(0)
	v_bfe_u32 v1, v2, 16, 1
	v_add3_u32 v1, v2, v1, s34
	ds_write_b16_d16_hi v13, v1 offset:64
	v_bfe_u32 v1, v3, 16, 1
	v_add3_u32 v1, v3, v1, s34
	ds_write_b16_d16_hi v13, v1 offset:208
	v_bfe_u32 v1, v4, 16, 1
	v_add3_u32 v1, v4, v1, s34
	ds_write_b16_d16_hi v13, v1 offset:352
	v_bfe_u32 v1, v5, 16, 1
	v_add3_u32 v1, v5, v1, s34
	ds_write_b16_d16_hi v13, v1 offset:496
	v_mov_b32_e32 v1, 0
	v_mov_b32_e32 v2, 0
	v_mov_b32_e32 v3, 0
	s_and_saveexec_b64 s[28:29], vcc
	s_cbranch_execz .LBB0_54
	v_or3_b32 v0, v11, v6, 48
	v_ashrrev_i32_e32 v1, 31, v0
	v_lshlrev_b64 v[0:1], 12, v[0:1]
	v_lshl_add_u64 v[0:1], v[8:9], 0, v[0:1]
	global_load_dwordx4 v[0:3], v[0:1], off nt

.LBB0_60:
	v_mov_b32_e32 v0, v184
	s_add_i32 s28, s63, 0xffffffa0
	v_ashrrev_i32_e32 v0, 8, v0
	v_add_u32_e32 v0, s28, v0
	v_mul_hi_i32 v1, v0, s37
	v_add_u32_e32 v1, v1, v0
	v_lshrrev_b32_e32 v2, 31, v1
	v_ashrrev_i32_e32 v1, 6, v1
	v_add_u32_e32 v3, v1, v2
	v_mul_lo_u32 v1, v3, s38
	v_sub_u32_e32 v0, v0, v1
	v_mov_b32_e32 v1, v184
	v_mov_b32_e32 v7, v184
	v_lshlrev_b32_e32 v10, 6, v0
	v_lshlrev_b32_e32 v2, 2, v7
	v_and_b32_e32 v13, 60, v2
	v_or_b32_e32 v2, v13, v10
	v_lshlrev_b32_e32 v6, 6, v3
	v_ashrrev_i32_e32 v3, 31, v2
	v_bfe_u32 v11, v7, 4, 4
	v_cmp_gt_i32_e32 vcc, s39, v2
	v_lshl_add_u64 v[8:9], v[2:3], 2, s[8:9]
	v_mov_b32_e32 v0, 0
	v_mov_b32_e32 v2, 0
	v_mov_b32_e32 v3, 0
	v_mov_b32_e32 v4, 0
	v_mov_b32_e32 v5, 0
	s_barrier
	s_and_saveexec_b64 s[28:29], vcc
	s_cbranch_execz .LBB0_62
	v_or_b32_e32 v2, v11, v6
	v_mad_i64_i32 v[2:3], s[64:65], v2, s40, v[8:9]
	global_load_dwordx4 v[2:5], v[2:3], off nt
.LBB0_62:
	s_or_b64 exec, exec, s[28:29]
	v_lshlrev_b32_e32 v1, 6, v1
	v_and_b32_e32 v12, 0xffffc000, v1
	v_mul_u32_u24_e32 v1, 0x90, v13
	v_or_b32_e32 v1, v12, v1
	s_waitcnt vmcnt(0)
	v_bfe_u32 v13, v2, 16, 1
	v_add3_u32 v2, v2, v13, s34
	v_lshl_add_u32 v13, v11, 1, v1
	v_bfe_u32 v1, v3, 16, 1
	v_add3_u32 v1, v3, v1, s34
	ds_write_b16_d16_hi v13, v1 offset:144
	v_bfe_u32 v1, v4, 16, 1
	v_add3_u32 v1, v4, v1, s34
	ds_write_b16_d16_hi v13, v1 offset:288
	v_bfe_u32 v1, v5, 16, 1
	v_add3_u32 v1, v5, v1, s34
	ds_write_b16_d16_hi v13, v2
	ds_write_b16_d16_hi v13, v1 offset:432
	v_mov_b32_e32 v1, 0
	v_mov_b32_e32 v2, 0
	v_mov_b32_e32 v3, 0
	s_and_saveexec_b64 s[28:29], vcc
	s_cbranch_execz .LBB0_64
	v_or3_b32 v0, v11, v6, 16
	v_mad_i64_i32 v[0:1], s[64:65], v0, s40, v[8:9]
	global_load_dwordx4 v[0:3], v[0:1], off nt
.LBB0_64:
	s_or_b64 exec, exec, s[28:29]
	s_waitcnt vmcnt(0)
	v_bfe_u32 v4, v0, 16, 1
	v_add3_u32 v0, v0, v4, s34
	ds_write_b16_d16_hi v13, v0 offset:32
	v_bfe_u32 v0, v1, 16, 1
	v_add3_u32 v0, v1, v0, s34
	ds_write_b16_d16_hi v13, v0 offset:176
	v_bfe_u32 v0, v2, 16, 1
	v_add3_u32 v0, v2, v0, s34
	ds_write_b16_d16_hi v13, v0 offset:320
	v_bfe_u32 v0, v3, 16, 1
	v_add3_u32 v0, v3, v0, s34
	ds_write_b16_d16_hi v13, v0 offset:464
	v_mov_b32_e32 v0, 0
	v_mov_b32_e32 v2, 0
	v_mov_b32_e32 v3, 0
	v_mov_b32_e32 v4, 0
	v_mov_b32_e32 v5, 0
	s_and_saveexec_b64 s[28:29], vcc
	s_cbranch_execz .LBB0_66
	v_or3_b32 v1, v11, v6, 32
	v_mad_i64_i32 v[2:3], s[64:65], v1, s40, v[8:9]
	global_load_dwordx4 v[2:5], v[2:3], off nt
.LBB0_66:
	s_or_b64 exec, exec, s[28:29]
	s_waitcnt vmcnt(0)
	v_bfe_u32 v1, v2, 16, 1
	v_add3_u32 v1, v2, v1, s34
	ds_write_b16_d16_hi v13, v1 offset:64
	v_bfe_u32 v1, v3, 16, 1
	v_add3_u32 v1, v3, v1, s34
	ds_write_b16_d16_hi v13, v1 offset:208
	v_bfe_u32 v1, v4, 16, 1
	v_add3_u32 v1, v4, v1, s34
	ds_write_b16_d16_hi v13, v1 offset:352
	v_bfe_u32 v1, v5, 16, 1
	v_add3_u32 v1, v5, v1, s34
	ds_write_b16_d16_hi v13, v1 offset:496
	v_mov_b32_e32 v1, 0
	v_mov_b32_e32 v2, 0
	v_mov_b32_e32 v3, 0
	s_and_saveexec_b64 s[28:29], vcc
	s_cbranch_execz .LBB0_68
	v_or3_b32 v0, v11, v6, 48
	v_mad_i64_i32 v[0:1], s[64:65], v0, s40, v[8:9]
	global_load_dwordx4 v[0:3], v[0:1], off nt

.LBB0_77:
	v_lshl_add_u64 v[56:57], v[54:55], 0, s[28:29]
	global_load_dwordx4 v[108:111], v[56:57], off nt
	v_add_co_u32_e32 v172, vcc, s46, v56
	s_nop 1
	v_addc_co_u32_e32 v173, vcc, 0, v57, vcc
	global_load_dwordx4 v[112:115], v[172:173], off nt
	v_add_co_u32_e32 v172, vcc, s47, v56
	s_nop 1
	v_addc_co_u32_e32 v173, vcc, 0, v57, vcc
	global_load_dwordx4 v[116:119], v[172:173], off nt
	v_add_co_u32_e32 v172, vcc, s48, v56
	s_nop 1
	v_addc_co_u32_e32 v173, vcc, 0, v57, vcc
	global_load_dwordx4 v[120:123], v[172:173], off nt
	v_add_co_u32_e32 v172, vcc, s49, v56
	s_nop 1
	v_addc_co_u32_e32 v173, vcc, 0, v57, vcc
	global_load_dwordx4 v[124:127], v[172:173], off nt
	v_add_co_u32_e32 v172, vcc, s50, v56
	s_nop 1
	v_addc_co_u32_e32 v173, vcc, 0, v57, vcc
	global_load_dwordx4 v[128:131], v[172:173], off nt
	v_add_co_u32_e32 v172, vcc, s51, v56
	s_nop 1
	v_addc_co_u32_e32 v173, vcc, 0, v57, vcc
	global_load_dwordx4 v[132:135], v[172:173], off nt
	v_add_co_u32_e32 v172, vcc, s52, v56
	s_nop 1
	v_addc_co_u32_e32 v173, vcc, 0, v57, vcc
	global_load_dwordx4 v[136:139], v[172:173], off nt
	v_add_co_u32_e32 v172, vcc, s53, v56
	s_nop 1
	v_addc_co_u32_e32 v173, vcc, 0, v57, vcc
	global_load_dwordx4 v[140:143], v[172:173], off nt
	v_add_co_u32_e32 v172, vcc, s54, v56
	s_nop 1
	v_addc_co_u32_e32 v173, vcc, 0, v57, vcc
	global_load_dwordx4 v[144:147], v[172:173], off nt
	v_add_co_u32_e32 v172, vcc, s55, v56
	s_nop 1
	v_addc_co_u32_e32 v173, vcc, 0, v57, vcc
	global_load_dwordx4 v[148:151], v[172:173], off nt
	v_add_co_u32_e32 v172, vcc, s56, v56
	s_nop 1
	v_addc_co_u32_e32 v173, vcc, 0, v57, vcc
	global_load_dwordx4 v[152:155], v[172:173], off nt
	v_add_co_u32_e32 v172, vcc, s57, v56
	s_nop 1
	v_addc_co_u32_e32 v173, vcc, 0, v57, vcc
	global_load_dwordx4 v[156:159], v[172:173], off nt
	v_add_co_u32_e32 v172, vcc, s58, v56
	s_nop 1
	v_addc_co_u32_e32 v173, vcc, 0, v57, vcc
	global_load_dwordx4 v[160:163], v[172:173], off nt
	v_add_co_u32_e32 v172, vcc, s59, v56
	s_nop 1
	v_addc_co_u32_e32 v173, vcc, 0, v57, vcc
	global_load_dwordx4 v[164:167], v[172:173], off nt
	v_add_co_u32_e32 v172, vcc, s60, v56
	s_nop 1
	v_addc_co_u32_e32 v173, vcc, 0, v57, vcc
	global_load_dwordx4 v[168:171], v[172:173], off nt
	ds_read_b128 v[58:61], v71
	ds_read_b128 v[44:47], v71 offset:16
	ds_read_b128 v[40:43], v71 offset:32
	ds_read_b128 v[36:39], v71 offset:48
	s_add_u32 s28, s28, 0x60000
	s_addc_u32 s29, s29, 0
	s_cmp_eq_u32 s28, 0x300000
	s_waitcnt vmcnt(15) lgkmcnt(3)
	v_pk_fma_f32 v[76:77], v[108:109], v[58:59], v[32:33] op_sel_hi:[1, 0, 1]
	v_pk_fma_f32 v[78:79], v[110:111], v[58:59], v[34:35] op_sel_hi:[1, 0, 1]
	ds_read_b128 v[32:35], v71 offset:4096
	s_waitcnt lgkmcnt(0)
	v_pk_fma_f32 v[80:81], v[108:109], v[32:33], v[28:29] op_sel_hi:[1, 0, 1]
	v_pk_fma_f32 v[82:83], v[110:111], v[32:33], v[30:31] op_sel_hi:[1, 0, 1]
	ds_read_b128 v[28:31], v71 offset:8192
	s_waitcnt lgkmcnt(0)
	v_pk_fma_f32 v[84:85], v[108:109], v[28:29], v[24:25] op_sel_hi:[1, 0, 1]
	v_pk_fma_f32 v[86:87], v[110:111], v[28:29], v[26:27] op_sel_hi:[1, 0, 1]
	ds_read_b128 v[24:27], v71 offset:12288
	s_waitcnt lgkmcnt(0)
	v_pk_fma_f32 v[88:89], v[108:109], v[24:25], v[20:21] op_sel_hi:[1, 0, 1]
	v_pk_fma_f32 v[90:91], v[110:111], v[24:25], v[22:23] op_sel_hi:[1, 0, 1]
	ds_read_b128 v[20:23], v71 offset:16384
	s_waitcnt lgkmcnt(0)
	v_pk_fma_f32 v[92:93], v[108:109], v[20:21], v[16:17] op_sel_hi:[1, 0, 1]
	v_pk_fma_f32 v[94:95], v[110:111], v[20:21], v[18:19] op_sel_hi:[1, 0, 1]
	ds_read_b128 v[16:19], v71 offset:20480
	s_waitcnt lgkmcnt(0)
	v_pk_fma_f32 v[96:97], v[108:109], v[16:17], v[12:13] op_sel_hi:[1, 0, 1]
	v_pk_fma_f32 v[98:99], v[110:111], v[16:17], v[14:15] op_sel_hi:[1, 0, 1]
	ds_read_b128 v[12:15], v71 offset:24576
	s_waitcnt lgkmcnt(0)
	v_pk_fma_f32 v[100:101], v[108:109], v[12:13], v[8:9] op_sel_hi:[1, 0, 1]
	v_pk_fma_f32 v[102:103], v[110:111], v[12:13], v[10:11] op_sel_hi:[1, 0, 1]
	ds_read_b128 v[8:11], v71 offset:28672
	s_waitcnt lgkmcnt(0)
	v_pk_fma_f32 v[104:105], v[108:109], v[8:9], v[4:5] op_sel_hi:[1, 0, 1]
	v_pk_fma_f32 v[106:107], v[110:111], v[8:9], v[6:7] op_sel_hi:[1, 0, 1]
	ds_read_b128 v[4:7], v71 offset:32768
	s_waitcnt lgkmcnt(0)
	v_pk_fma_f32 v[72:73], v[108:109], v[4:5], v[0:1] op_sel_hi:[1, 0, 1]
	v_pk_fma_f32 v[74:75], v[110:111], v[4:5], v[2:3] op_sel_hi:[1, 0, 1]
	s_nop 0
	s_waitcnt vmcnt(14)
	v_pk_fma_f32 v[76:77], v[112:113], v[58:59], v[76:77] op_sel:[0, 1, 0]
	v_pk_fma_f32 v[58:59], v[114:115], v[58:59], v[78:79] op_sel:[0, 1, 0]
	v_pk_fma_f32 v[78:79], v[112:113], v[32:33], v[80:81] op_sel:[0, 1, 0]
	v_pk_fma_f32 v[32:33], v[114:115], v[32:33], v[82:83] op_sel:[0, 1, 0]
	v_pk_fma_f32 v[80:81], v[112:113], v[28:29], v[84:85] op_sel:[0, 1, 0]
	v_pk_fma_f32 v[28:29], v[114:115], v[28:29], v[86:87] op_sel:[0, 1, 0]
	v_pk_fma_f32 v[82:83], v[112:113], v[24:25], v[88:89] op_sel:[0, 1, 0]
	v_pk_fma_f32 v[24:25], v[114:115], v[24:25], v[90:91] op_sel:[0, 1, 0]
	v_pk_fma_f32 v[84:85], v[112:113], v[20:21], v[92:93] op_sel:[0, 1, 0]
	v_pk_fma_f32 v[86:87], v[112:113], v[16:17], v[96:97] op_sel:[0, 1, 0]
	v_pk_fma_f32 v[88:89], v[112:113], v[12:13], v[100:101] op_sel:[0, 1, 0]
	v_pk_fma_f32 v[90:91], v[112:113], v[8:9], v[104:105] op_sel:[0, 1, 0]
	v_pk_fma_f32 v[72:73], v[112:113], v[4:5], v[72:73] op_sel:[0, 1, 0]
	v_pk_fma_f32 v[20:21], v[114:115], v[20:21], v[94:95] op_sel:[0, 1, 0]
	s_nop 0
	v_pk_fma_f32 v[16:17], v[114:115], v[16:17], v[98:99] op_sel:[0, 1, 0]
	v_pk_fma_f32 v[12:13], v[114:115], v[12:13], v[102:103] op_sel:[0, 1, 0]
	v_pk_fma_f32 v[8:9], v[114:115], v[8:9], v[106:107] op_sel:[0, 1, 0]
	v_pk_fma_f32 v[4:5], v[114:115], v[4:5], v[74:75] op_sel:[0, 1, 0]
	s_waitcnt vmcnt(13)
	v_pk_fma_f32 v[74:75], v[116:117], v[60:61], v[76:77] op_sel_hi:[1, 0, 1]
	v_pk_fma_f32 v[76:77], v[116:117], v[34:35], v[78:79] op_sel_hi:[1, 0, 1]
	v_pk_fma_f32 v[78:79], v[116:117], v[30:31], v[80:81] op_sel_hi:[1, 0, 1]
	v_pk_fma_f32 v[80:81], v[116:117], v[26:27], v[82:83] op_sel_hi:[1, 0, 1]
	v_pk_fma_f32 v[82:83], v[116:117], v[22:23], v[84:85] op_sel_hi:[1, 0, 1]
	v_pk_fma_f32 v[84:85], v[116:117], v[18:19], v[86:87] op_sel_hi:[1, 0, 1]
	v_pk_fma_f32 v[86:87], v[116:117], v[14:15], v[88:89] op_sel_hi:[1, 0, 1]
	v_pk_fma_f32 v[88:89], v[116:117], v[10:11], v[90:91] op_sel_hi:[1, 0, 1]
	v_pk_fma_f32 v[72:73], v[116:117], v[6:7], v[72:73] op_sel_hi:[1, 0, 1]
	v_pk_fma_f32 v[58:59], v[118:119], v[60:61], v[58:59] op_sel_hi:[1, 0, 1]
	s_nop 0
	v_pk_fma_f32 v[32:33], v[118:119], v[34:35], v[32:33] op_sel_hi:[1, 0, 1]
	v_pk_fma_f32 v[28:29], v[118:119], v[30:31], v[28:29] op_sel_hi:[1, 0, 1]
	v_pk_fma_f32 v[24:25], v[118:119], v[26:27], v[24:25] op_sel_hi:[1, 0, 1]
	v_pk_fma_f32 v[20:21], v[118:119], v[22:23], v[20:21] op_sel_hi:[1, 0, 1]
	v_pk_fma_f32 v[16:17], v[118:119], v[18:19], v[16:17] op_sel_hi:[1, 0, 1]
	v_pk_fma_f32 v[12:13], v[118:119], v[14:15], v[12:13] op_sel_hi:[1, 0, 1]
	v_pk_fma_f32 v[8:9], v[118:119], v[10:11], v[8:9] op_sel_hi:[1, 0, 1]
	v_pk_fma_f32 v[90:91], v[118:119], v[6:7], v[4:5] op_sel_hi:[1, 0, 1]
	v_mov_b32_e32 v4, v61
	v_mov_b32_e32 v6, v7
	s_waitcnt vmcnt(12)
	v_pk_fma_f32 v[74:75], v[120:121], v[4:5], v[74:75] op_sel_hi:[1, 0, 1]
	v_pk_fma_f32 v[92:93], v[122:123], v[4:5], v[58:59] op_sel_hi:[1, 0, 1]
	v_mov_b32_e32 v4, v35
	v_pk_fma_f32 v[58:59], v[120:121], v[4:5], v[76:77] op_sel_hi:[1, 0, 1]
	v_pk_fma_f32 v[60:61], v[122:123], v[4:5], v[32:33] op_sel_hi:[1, 0, 1]
	v_mov_b32_e32 v4, v31
	v_pk_fma_f32 v[32:33], v[120:121], v[4:5], v[78:79] op_sel_hi:[1, 0, 1]
	v_pk_fma_f32 v[34:35], v[122:123], v[4:5], v[28:29] op_sel_hi:[1, 0, 1]
	v_mov_b32_e32 v4, v27
	v_pk_fma_f32 v[28:29], v[120:121], v[4:5], v[80:81] op_sel_hi:[1, 0, 1]
	v_pk_fma_f32 v[30:31], v[122:123], v[4:5], v[24:25] op_sel_hi:[1, 0, 1]
	v_mov_b32_e32 v4, v23
	v_pk_fma_f32 v[24:25], v[120:121], v[4:5], v[82:83] op_sel_hi:[1, 0, 1]
	v_pk_fma_f32 v[26:27], v[122:123], v[4:5], v[20:21] op_sel_hi:[1, 0, 1]
	v_mov_b32_e32 v4, v19
	v_pk_fma_f32 v[20:21], v[120:121], v[4:5], v[84:85] op_sel_hi:[1, 0, 1]
	v_pk_fma_f32 v[22:23], v[122:123], v[4:5], v[16:17] op_sel_hi:[1, 0, 1]
	v_mov_b32_e32 v4, v15
	v_pk_fma_f32 v[16:17], v[120:121], v[4:5], v[86:87] op_sel_hi:[1, 0, 1]
	v_pk_fma_f32 v[18:19], v[122:123], v[4:5], v[12:13] op_sel_hi:[1, 0, 1]
	v_mov_b32_e32 v4, v11
	v_pk_fma_f32 v[12:13], v[120:121], v[4:5], v[88:89] op_sel_hi:[1, 0, 1]
	v_pk_fma_f32 v[14:15], v[122:123], v[4:5], v[8:9] op_sel_hi:[1, 0, 1]
	v_pk_fma_f32 v[4:5], v[120:121], v[6:7], v[72:73] op_sel_hi:[1, 0, 1]
	v_pk_fma_f32 v[6:7], v[122:123], v[6:7], v[90:91] op_sel_hi:[1, 0, 1]
	s_nop 0
	ds_read_b128 v[84:87], v71 offset:32784
	ds_read_b128 v[76:79], v71 offset:24592
	ds_read_b128 v[80:83], v71 offset:28688
	s_waitcnt vmcnt(11)
	v_pk_fma_f32 v[8:9], v[124:125], v[44:45], v[74:75] op_sel_hi:[1, 0, 1]
	ds_read_b128 v[72:75], v71 offset:4112
	v_pk_fma_f32 v[10:11], v[126:127], v[44:45], v[92:93] op_sel_hi:[1, 0, 1]
	s_waitcnt lgkmcnt(2)
	v_pk_fma_f32 v[16:17], v[124:125], v[76:77], v[16:17] op_sel_hi:[1, 0, 1]
	s_waitcnt lgkmcnt(1)
	v_pk_fma_f32 v[12:13], v[124:125], v[80:81], v[12:13] op_sel_hi:[1, 0, 1]
	v_pk_fma_f32 v[4:5], v[124:125], v[84:85], v[4:5] op_sel_hi:[1, 0, 1]
	s_waitcnt lgkmcnt(0)
	v_pk_fma_f32 v[88:89], v[124:125], v[72:73], v[58:59] op_sel_hi:[1, 0, 1]
	v_pk_fma_f32 v[90:91], v[126:127], v[72:73], v[60:61] op_sel_hi:[1, 0, 1]
	ds_read_b128 v[58:61], v71 offset:8208
	v_pk_fma_f32 v[18:19], v[126:127], v[76:77], v[18:19] op_sel_hi:[1, 0, 1]
	v_pk_fma_f32 v[14:15], v[126:127], v[80:81], v[14:15] op_sel_hi:[1, 0, 1]
	v_pk_fma_f32 v[6:7], v[126:127], v[84:85], v[6:7] op_sel_hi:[1, 0, 1]
	s_waitcnt lgkmcnt(0)
	v_pk_fma_f32 v[92:93], v[124:125], v[58:59], v[32:33] op_sel_hi:[1, 0, 1]
	v_pk_fma_f32 v[94:95], v[126:127], v[58:59], v[34:35] op_sel_hi:[1, 0, 1]
	ds_read_b128 v[32:35], v71 offset:12304
	s_waitcnt lgkmcnt(0)
	v_pk_fma_f32 v[96:97], v[124:125], v[32:33], v[28:29] op_sel_hi:[1, 0, 1]
	v_pk_fma_f32 v[98:99], v[126:127], v[32:33], v[30:31] op_sel_hi:[1, 0, 1]
	ds_read_b128 v[28:31], v71 offset:16400
	s_waitcnt lgkmcnt(0)
	v_pk_fma_f32 v[100:101], v[124:125], v[28:29], v[24:25] op_sel_hi:[1, 0, 1]
	v_pk_fma_f32 v[102:103], v[126:127], v[28:29], v[26:27] op_sel_hi:[1, 0, 1]
	ds_read_b128 v[24:27], v71 offset:20496
	s_waitcnt lgkmcnt(0)
	v_pk_fma_f32 v[20:21], v[124:125], v[24:25], v[20:21] op_sel_hi:[1, 0, 1]
	v_pk_fma_f32 v[22:23], v[126:127], v[24:25], v[22:23] op_sel_hi:[1, 0, 1]
	s_nop 0
	s_waitcnt vmcnt(10)
	v_pk_fma_f32 v[8:9], v[128:129], v[44:45], v[8:9] op_sel:[0, 1, 0]
	v_pk_fma_f32 v[10:11], v[130:131], v[44:45], v[10:11] op_sel:[0, 1, 0]
	v_pk_fma_f32 v[44:45], v[128:129], v[72:73], v[88:89] op_sel:[0, 1, 0]
	v_pk_fma_f32 v[72:73], v[130:131], v[72:73], v[90:91] op_sel:[0, 1, 0]
	v_pk_fma_f32 v[88:89], v[128:129], v[58:59], v[92:93] op_sel:[0, 1, 0]
	v_pk_fma_f32 v[90:91], v[128:129], v[32:33], v[96:97] op_sel:[0, 1, 0]
	v_pk_fma_f32 v[92:93], v[128:129], v[28:29], v[100:101] op_sel:[0, 1, 0]
	v_pk_fma_f32 v[20:21], v[128:129], v[24:25], v[20:21] op_sel:[0, 1, 0]
	v_pk_fma_f32 v[16:17], v[128:129], v[76:77], v[16:17] op_sel:[0, 1, 0]
	v_pk_fma_f32 v[12:13], v[128:129], v[80:81], v[12:13] op_sel:[0, 1, 0]
	v_pk_fma_f32 v[4:5], v[128:129], v[84:85], v[4:5] op_sel:[0, 1, 0]
	v_pk_fma_f32 v[58:59], v[130:131], v[58:59], v[94:95] op_sel:[0, 1, 0]
	s_nop 0
	v_pk_fma_f32 v[32:33], v[130:131], v[32:33], v[98:99] op_sel:[0, 1, 0]
	v_pk_fma_f32 v[28:29], v[130:131], v[28:29], v[102:103] op_sel:[0, 1, 0]
	v_pk_fma_f32 v[22:23], v[130:131], v[24:25], v[22:23] op_sel:[0, 1, 0]
	v_pk_fma_f32 v[18:19], v[130:131], v[76:77], v[18:19] op_sel:[0, 1, 0]
	v_pk_fma_f32 v[14:15], v[130:131], v[80:81], v[14:15] op_sel:[0, 1, 0]
	v_pk_fma_f32 v[6:7], v[130:131], v[84:85], v[6:7] op_sel:[0, 1, 0]
	s_waitcnt vmcnt(9)
	v_pk_fma_f32 v[8:9], v[132:133], v[46:47], v[8:9] op_sel_hi:[1, 0, 1]
	v_pk_fma_f32 v[24:25], v[132:133], v[74:75], v[44:45] op_sel_hi:[1, 0, 1]
	v_pk_fma_f32 v[44:45], v[134:135], v[74:75], v[72:73] op_sel_hi:[1, 0, 1]
	v_pk_fma_f32 v[72:73], v[132:133], v[60:61], v[88:89] op_sel_hi:[1, 0, 1]
	v_pk_fma_f32 v[76:77], v[132:133], v[34:35], v[90:91] op_sel_hi:[1, 0, 1]
	v_pk_fma_f32 v[80:81], v[132:133], v[30:31], v[92:93] op_sel_hi:[1, 0, 1]
	v_pk_fma_f32 v[20:21], v[132:133], v[26:27], v[20:21] op_sel_hi:[1, 0, 1]
	v_pk_fma_f32 v[84:85], v[132:133], v[78:79], v[16:17] op_sel_hi:[1, 0, 1]
	v_pk_fma_f32 v[90:91], v[132:133], v[82:83], v[12:13] op_sel_hi:[1, 0, 1]
	v_pk_fma_f32 v[94:95], v[132:133], v[86:87], v[4:5] op_sel_hi:[1, 0, 1]
	v_pk_fma_f32 v[10:11], v[134:135], v[46:47], v[10:11] op_sel_hi:[1, 0, 1]
	s_nop 0
	v_pk_fma_f32 v[58:59], v[134:135], v[60:61], v[58:59] op_sel_hi:[1, 0, 1]
	v_pk_fma_f32 v[32:33], v[134:135], v[34:35], v[32:33] op_sel_hi:[1, 0, 1]
	v_pk_fma_f32 v[28:29], v[134:135], v[30:31], v[28:29] op_sel_hi:[1, 0, 1]
	v_pk_fma_f32 v[22:23], v[134:135], v[26:27], v[22:23] op_sel_hi:[1, 0, 1]
	v_pk_fma_f32 v[88:89], v[134:135], v[78:79], v[18:19] op_sel_hi:[1, 0, 1]
	v_pk_fma_f32 v[92:93], v[134:135], v[82:83], v[14:15] op_sel_hi:[1, 0, 1]
	v_pk_fma_f32 v[96:97], v[134:135], v[86:87], v[6:7] op_sel_hi:[1, 0, 1]
	v_mov_b32_e32 v4, v47
	v_mov_b32_e32 v6, v75
	v_mov_b32_e32 v14, v35
	v_mov_b32_e32 v18, v31
	v_mov_b32_e32 v26, v79
	v_mov_b32_e32 v30, v83
	v_mov_b32_e32 v34, v87
	s_waitcnt vmcnt(8)
	v_pk_fma_f32 v[46:47], v[136:137], v[4:5], v[8:9] op_sel_hi:[1, 0, 1]
	v_pk_fma_f32 v[98:99], v[138:139], v[4:5], v[10:11] op_sel_hi:[1, 0, 1]
	v_pk_fma_f32 v[4:5], v[136:137], v[6:7], v[24:25] op_sel_hi:[1, 0, 1]
	v_mov_b32_e32 v10, v61
	v_mov_b32_e32 v24, v27
	v_pk_fma_f32 v[8:9], v[136:137], v[10:11], v[72:73] op_sel_hi:[1, 0, 1]
	v_pk_fma_f32 v[12:13], v[136:137], v[14:15], v[76:77] op_sel_hi:[1, 0, 1]
	v_pk_fma_f32 v[14:15], v[138:139], v[14:15], v[32:33] op_sel_hi:[1, 0, 1]
	v_pk_fma_f32 v[16:17], v[136:137], v[18:19], v[80:81] op_sel_hi:[1, 0, 1]
	v_pk_fma_f32 v[18:19], v[138:139], v[18:19], v[28:29] op_sel_hi:[1, 0, 1]
	v_pk_fma_f32 v[20:21], v[136:137], v[24:25], v[20:21] op_sel_hi:[1, 0, 1]
	v_pk_fma_f32 v[22:23], v[138:139], v[24:25], v[22:23] op_sel_hi:[1, 0, 1]
	v_pk_fma_f32 v[24:25], v[136:137], v[26:27], v[84:85] op_sel_hi:[1, 0, 1]
	v_pk_fma_f32 v[28:29], v[136:137], v[30:31], v[90:91] op_sel_hi:[1, 0, 1]
	v_pk_fma_f32 v[32:33], v[136:137], v[34:35], v[94:95] op_sel_hi:[1, 0, 1]
	v_pk_fma_f32 v[6:7], v[138:139], v[6:7], v[44:45] op_sel_hi:[1, 0, 1]
	s_nop 0
	v_pk_fma_f32 v[10:11], v[138:139], v[10:11], v[58:59] op_sel_hi:[1, 0, 1]
	v_pk_fma_f32 v[26:27], v[138:139], v[26:27], v[88:89] op_sel_hi:[1, 0, 1]
	v_pk_fma_f32 v[30:31], v[138:139], v[30:31], v[92:93] op_sel_hi:[1, 0, 1]
	v_pk_fma_f32 v[34:35], v[138:139], v[34:35], v[96:97] op_sel_hi:[1, 0, 1]
	ds_read_b128 v[58:61], v71 offset:4128
	ds_read_b128 v[80:83], v71 offset:32800
	ds_read_b128 v[72:75], v71 offset:24608
	ds_read_b128 v[76:79], v71 offset:28704
	s_waitcnt vmcnt(7) lgkmcnt(3)
	v_pk_fma_f32 v[84:85], v[140:141], v[58:59], v[4:5] op_sel_hi:[1, 0, 1]
	v_pk_fma_f32 v[86:87], v[142:143], v[58:59], v[6:7] op_sel_hi:[1, 0, 1]
	ds_read_b128 v[4:7], v71 offset:8224
	v_pk_fma_f32 v[44:45], v[140:141], v[40:41], v[46:47] op_sel_hi:[1, 0, 1]
	v_pk_fma_f32 v[46:47], v[142:143], v[40:41], v[98:99] op_sel_hi:[1, 0, 1]
	s_waitcnt lgkmcnt(2)
	v_pk_fma_f32 v[24:25], v[140:141], v[72:73], v[24:25] op_sel_hi:[1, 0, 1]
	s_waitcnt lgkmcnt(1)
	v_pk_fma_f32 v[28:29], v[140:141], v[76:77], v[28:29] op_sel_hi:[1, 0, 1]
	s_waitcnt lgkmcnt(0)
	v_pk_fma_f32 v[88:89], v[140:141], v[4:5], v[8:9] op_sel_hi:[1, 0, 1]
	v_pk_fma_f32 v[90:91], v[142:143], v[4:5], v[10:11] op_sel_hi:[1, 0, 1]
	ds_read_b128 v[8:11], v71 offset:12320
	v_pk_fma_f32 v[32:33], v[140:141], v[80:81], v[32:33] op_sel_hi:[1, 0, 1]
	v_pk_fma_f32 v[26:27], v[142:143], v[72:73], v[26:27] op_sel_hi:[1, 0, 1]
	v_pk_fma_f32 v[30:31], v[142:143], v[76:77], v[30:31] op_sel_hi:[1, 0, 1]
	v_pk_fma_f32 v[34:35], v[142:143], v[80:81], v[34:35] op_sel_hi:[1, 0, 1]
	s_waitcnt lgkmcnt(0)
	v_pk_fma_f32 v[92:93], v[140:141], v[8:9], v[12:13] op_sel_hi:[1, 0, 1]
	v_pk_fma_f32 v[94:95], v[142:143], v[8:9], v[14:15] op_sel_hi:[1, 0, 1]
	ds_read_b128 v[12:15], v71 offset:16416
	s_waitcnt lgkmcnt(0)
	v_pk_fma_f32 v[96:97], v[140:141], v[12:13], v[16:17] op_sel_hi:[1, 0, 1]
	v_pk_fma_f32 v[98:99], v[142:143], v[12:13], v[18:19] op_sel_hi:[1, 0, 1]
	ds_read_b128 v[16:19], v71 offset:20512
	s_waitcnt lgkmcnt(0)
	v_pk_fma_f32 v[20:21], v[140:141], v[16:17], v[20:21] op_sel_hi:[1, 0, 1]
	v_pk_fma_f32 v[22:23], v[142:143], v[16:17], v[22:23] op_sel_hi:[1, 0, 1]
	s_nop 0
	s_waitcnt vmcnt(6)
	v_pk_fma_f32 v[44:45], v[144:145], v[40:41], v[44:45] op_sel:[0, 1, 0]
	v_pk_fma_f32 v[40:41], v[146:147], v[40:41], v[46:47] op_sel:[0, 1, 0]
	v_pk_fma_f32 v[46:47], v[144:145], v[58:59], v[84:85] op_sel:[0, 1, 0]
	v_pk_fma_f32 v[58:59], v[146:147], v[58:59], v[86:87] op_sel:[0, 1, 0]
	v_pk_fma_f32 v[84:85], v[144:145], v[4:5], v[88:89] op_sel:[0, 1, 0]
	v_pk_fma_f32 v[86:87], v[144:145], v[8:9], v[92:93] op_sel:[0, 1, 0]
	v_pk_fma_f32 v[88:89], v[144:145], v[12:13], v[96:97] op_sel:[0, 1, 0]
	v_pk_fma_f32 v[20:21], v[144:145], v[16:17], v[20:21] op_sel:[0, 1, 0]
	v_pk_fma_f32 v[16:17], v[146:147], v[16:17], v[22:23] op_sel:[0, 1, 0]
	v_pk_fma_f32 v[22:23], v[144:145], v[72:73], v[24:25] op_sel:[0, 1, 0]
	v_pk_fma_f32 v[24:25], v[146:147], v[72:73], v[26:27] op_sel:[0, 1, 0]
	v_pk_fma_f32 v[26:27], v[144:145], v[76:77], v[28:29] op_sel:[0, 1, 0]
	v_pk_fma_f32 v[28:29], v[146:147], v[76:77], v[30:31] op_sel:[0, 1, 0]
	v_pk_fma_f32 v[30:31], v[144:145], v[80:81], v[32:33] op_sel:[0, 1, 0]
	v_pk_fma_f32 v[4:5], v[146:147], v[4:5], v[90:91] op_sel:[0, 1, 0]
	s_nop 0
	v_pk_fma_f32 v[8:9], v[146:147], v[8:9], v[94:95] op_sel:[0, 1, 0]
	v_pk_fma_f32 v[12:13], v[146:147], v[12:13], v[98:99] op_sel:[0, 1, 0]
	v_pk_fma_f32 v[32:33], v[146:147], v[80:81], v[34:35] op_sel:[0, 1, 0]
	s_waitcnt vmcnt(5)
	v_pk_fma_f32 v[34:35], v[148:149], v[42:43], v[44:45] op_sel_hi:[1, 0, 1]
	v_pk_fma_f32 v[44:45], v[148:149], v[60:61], v[46:47] op_sel_hi:[1, 0, 1]
	v_pk_fma_f32 v[46:47], v[150:151], v[60:61], v[58:59] op_sel_hi:[1, 0, 1]
	v_pk_fma_f32 v[58:59], v[148:149], v[6:7], v[84:85] op_sel_hi:[1, 0, 1]
	v_pk_fma_f32 v[72:73], v[148:149], v[10:11], v[86:87] op_sel_hi:[1, 0, 1]
	v_pk_fma_f32 v[76:77], v[148:149], v[14:15], v[88:89] op_sel_hi:[1, 0, 1]
	v_pk_fma_f32 v[20:21], v[148:149], v[18:19], v[20:21] op_sel_hi:[1, 0, 1]
	v_pk_fma_f32 v[80:81], v[148:149], v[74:75], v[22:23] op_sel_hi:[1, 0, 1]
	v_pk_fma_f32 v[86:87], v[148:149], v[78:79], v[26:27] op_sel_hi:[1, 0, 1]
	v_pk_fma_f32 v[90:91], v[148:149], v[82:83], v[30:31] op_sel_hi:[1, 0, 1]
	v_pk_fma_f32 v[40:41], v[150:151], v[42:43], v[40:41] op_sel_hi:[1, 0, 1]
	s_nop 0
	v_pk_fma_f32 v[4:5], v[150:151], v[6:7], v[4:5] op_sel_hi:[1, 0, 1]
	v_pk_fma_f32 v[8:9], v[150:151], v[10:11], v[8:9] op_sel_hi:[1, 0, 1]
	v_pk_fma_f32 v[12:13], v[150:151], v[14:15], v[12:13] op_sel_hi:[1, 0, 1]
	v_pk_fma_f32 v[16:17], v[150:151], v[18:19], v[16:17] op_sel_hi:[1, 0, 1]
	v_pk_fma_f32 v[84:85], v[150:151], v[74:75], v[24:25] op_sel_hi:[1, 0, 1]
	v_pk_fma_f32 v[88:89], v[150:151], v[78:79], v[28:29] op_sel_hi:[1, 0, 1]
	v_pk_fma_f32 v[92:93], v[150:151], v[82:83], v[32:33] op_sel_hi:[1, 0, 1]
	v_mov_b32_e32 v6, v43
	s_waitcnt vmcnt(4)
	v_pk_fma_f32 v[94:95], v[152:153], v[6:7], v[34:35] op_sel_hi:[1, 0, 1]
	v_pk_fma_f32 v[96:97], v[154:155], v[6:7], v[40:41] op_sel_hi:[1, 0, 1]
	v_mov_b32_e32 v6, v61
	v_pk_fma_f32 v[40:41], v[152:153], v[6:7], v[44:45] op_sel_hi:[1, 0, 1]
	v_pk_fma_f32 v[42:43], v[154:155], v[6:7], v[46:47] op_sel_hi:[1, 0, 1]
	v_mov_b32_e32 v6, v7
	v_pk_fma_f32 v[34:35], v[154:155], v[6:7], v[4:5] op_sel_hi:[1, 0, 1]
	v_mov_b32_e32 v4, v11
	v_pk_fma_f32 v[28:29], v[152:153], v[4:5], v[72:73] op_sel_hi:[1, 0, 1]
	v_pk_fma_f32 v[30:31], v[154:155], v[4:5], v[8:9] op_sel_hi:[1, 0, 1]
	v_mov_b32_e32 v4, v15
	v_pk_fma_f32 v[24:25], v[152:153], v[4:5], v[76:77] op_sel_hi:[1, 0, 1]
	v_pk_fma_f32 v[26:27], v[154:155], v[4:5], v[12:13] op_sel_hi:[1, 0, 1]
	v_mov_b32_e32 v4, v19
	v_pk_fma_f32 v[20:21], v[152:153], v[4:5], v[20:21] op_sel_hi:[1, 0, 1]
	v_pk_fma_f32 v[22:23], v[154:155], v[4:5], v[16:17] op_sel_hi:[1, 0, 1]
	v_mov_b32_e32 v4, v75
	v_pk_fma_f32 v[32:33], v[152:153], v[6:7], v[58:59] op_sel_hi:[1, 0, 1]
	v_pk_fma_f32 v[16:17], v[152:153], v[4:5], v[80:81] op_sel_hi:[1, 0, 1]
	v_pk_fma_f32 v[18:19], v[154:155], v[4:5], v[84:85] op_sel_hi:[1, 0, 1]
	v_mov_b32_e32 v4, v79
	v_mov_b32_e32 v6, v83
	v_pk_fma_f32 v[12:13], v[152:153], v[4:5], v[86:87] op_sel_hi:[1, 0, 1]
	v_pk_fma_f32 v[14:15], v[154:155], v[4:5], v[88:89] op_sel_hi:[1, 0, 1]
	v_pk_fma_f32 v[4:5], v[152:153], v[6:7], v[90:91] op_sel_hi:[1, 0, 1]
	v_pk_fma_f32 v[6:7], v[154:155], v[6:7], v[92:93] op_sel_hi:[1, 0, 1]
	s_nop 0
	ds_read_b128 v[44:47], v71 offset:4144
	ds_read_b128 v[88:91], v71 offset:32816
	ds_read_b128 v[58:61], v71 offset:12336
	ds_read_b128 v[72:75], v71 offset:16432
	ds_read_b128 v[76:79], v71 offset:20528
	ds_read_b128 v[80:83], v71 offset:24624
	ds_read_b128 v[84:87], v71 offset:28720
	s_waitcnt vmcnt(3)
	v_pk_fma_f32 v[8:9], v[156:157], v[36:37], v[94:95] op_sel_hi:[1, 0, 1]
	s_waitcnt lgkmcnt(6)
	v_pk_fma_f32 v[92:93], v[156:157], v[44:45], v[40:41] op_sel_hi:[1, 0, 1]
	v_pk_fma_f32 v[94:95], v[158:159], v[44:45], v[42:43] op_sel_hi:[1, 0, 1]
	ds_read_b128 v[40:43], v71 offset:8240
	s_waitcnt lgkmcnt(5)
	v_pk_fma_f32 v[28:29], v[156:157], v[58:59], v[28:29] op_sel_hi:[1, 0, 1]
	s_waitcnt lgkmcnt(4)
	v_pk_fma_f32 v[24:25], v[156:157], v[72:73], v[24:25] op_sel_hi:[1, 0, 1]
	s_waitcnt lgkmcnt(3)
	v_pk_fma_f32 v[20:21], v[156:157], v[76:77], v[20:21] op_sel_hi:[1, 0, 1]
	s_waitcnt lgkmcnt(2)
	v_pk_fma_f32 v[16:17], v[156:157], v[80:81], v[16:17] op_sel_hi:[1, 0, 1]
	s_waitcnt lgkmcnt(0)
	v_pk_fma_f32 v[32:33], v[156:157], v[40:41], v[32:33] op_sel_hi:[1, 0, 1]
	v_pk_fma_f32 v[12:13], v[156:157], v[84:85], v[12:13] op_sel_hi:[1, 0, 1]
	v_pk_fma_f32 v[4:5], v[156:157], v[88:89], v[4:5] op_sel_hi:[1, 0, 1]
	v_pk_fma_f32 v[10:11], v[158:159], v[36:37], v[96:97] op_sel_hi:[1, 0, 1]
	s_nop 0
	v_pk_fma_f32 v[34:35], v[158:159], v[40:41], v[34:35] op_sel_hi:[1, 0, 1]
	v_pk_fma_f32 v[30:31], v[158:159], v[58:59], v[30:31] op_sel_hi:[1, 0, 1]
	v_pk_fma_f32 v[26:27], v[158:159], v[72:73], v[26:27] op_sel_hi:[1, 0, 1]
	v_pk_fma_f32 v[22:23], v[158:159], v[76:77], v[22:23] op_sel_hi:[1, 0, 1]
	v_pk_fma_f32 v[18:19], v[158:159], v[80:81], v[18:19] op_sel_hi:[1, 0, 1]
	v_pk_fma_f32 v[14:15], v[158:159], v[84:85], v[14:15] op_sel_hi:[1, 0, 1]
	v_pk_fma_f32 v[6:7], v[158:159], v[88:89], v[6:7] op_sel_hi:[1, 0, 1]
	v_add_u32_e32 v71, 64, v71
	s_waitcnt vmcnt(2)
	v_pk_fma_f32 v[8:9], v[160:161], v[36:37], v[8:9] op_sel:[0, 1, 0]
	v_pk_fma_f32 v[10:11], v[162:163], v[36:37], v[10:11] op_sel:[0, 1, 0]
	v_pk_fma_f32 v[36:37], v[160:161], v[44:45], v[92:93] op_sel:[0, 1, 0]
	v_pk_fma_f32 v[32:33], v[160:161], v[40:41], v[32:33] op_sel:[0, 1, 0]
	v_pk_fma_f32 v[28:29], v[160:161], v[58:59], v[28:29] op_sel:[0, 1, 0]
	v_pk_fma_f32 v[24:25], v[160:161], v[72:73], v[24:25] op_sel:[0, 1, 0]
	v_pk_fma_f32 v[20:21], v[160:161], v[76:77], v[20:21] op_sel:[0, 1, 0]
	v_pk_fma_f32 v[16:17], v[160:161], v[80:81], v[16:17] op_sel:[0, 1, 0]
	v_pk_fma_f32 v[12:13], v[160:161], v[84:85], v[12:13] op_sel:[0, 1, 0]
	v_pk_fma_f32 v[4:5], v[160:161], v[88:89], v[4:5] op_sel:[0, 1, 0]
	v_pk_fma_f32 v[44:45], v[162:163], v[44:45], v[94:95] op_sel:[0, 1, 0]
	s_nop 0
	v_pk_fma_f32 v[34:35], v[162:163], v[40:41], v[34:35] op_sel:[0, 1, 0]
	v_pk_fma_f32 v[30:31], v[162:163], v[58:59], v[30:31] op_sel:[0, 1, 0]
	v_pk_fma_f32 v[26:27], v[162:163], v[72:73], v[26:27] op_sel:[0, 1, 0]
	v_pk_fma_f32 v[22:23], v[162:163], v[76:77], v[22:23] op_sel:[0, 1, 0]
	v_pk_fma_f32 v[18:19], v[162:163], v[80:81], v[18:19] op_sel:[0, 1, 0]
	v_pk_fma_f32 v[14:15], v[162:163], v[84:85], v[14:15] op_sel:[0, 1, 0]
	v_pk_fma_f32 v[6:7], v[162:163], v[88:89], v[6:7] op_sel:[0, 1, 0]
	s_waitcnt vmcnt(1)
	v_pk_fma_f32 v[8:9], v[164:165], v[38:39], v[8:9] op_sel_hi:[1, 0, 1]
	v_pk_fma_f32 v[36:37], v[164:165], v[46:47], v[36:37] op_sel_hi:[1, 0, 1]
	v_pk_fma_f32 v[40:41], v[166:167], v[46:47], v[44:45] op_sel_hi:[1, 0, 1]
	v_pk_fma_f32 v[44:45], v[164:165], v[42:43], v[32:33] op_sel_hi:[1, 0, 1]
	v_pk_fma_f32 v[72:73], v[164:165], v[60:61], v[28:29] op_sel_hi:[1, 0, 1]
	v_pk_fma_f32 v[80:81], v[164:165], v[74:75], v[24:25] op_sel_hi:[1, 0, 1]
	v_pk_fma_f32 v[88:89], v[164:165], v[78:79], v[20:21] op_sel_hi:[1, 0, 1]
	v_pk_fma_f32 v[94:95], v[164:165], v[82:83], v[16:17] op_sel_hi:[1, 0, 1]
	v_pk_fma_f32 v[98:99], v[164:165], v[86:87], v[12:13] op_sel_hi:[1, 0, 1]
	v_pk_fma_f32 v[102:103], v[164:165], v[90:91], v[4:5] op_sel_hi:[1, 0, 1]
	v_pk_fma_f32 v[10:11], v[166:167], v[38:39], v[10:11] op_sel_hi:[1, 0, 1]
	s_nop 0
	v_pk_fma_f32 v[58:59], v[166:167], v[42:43], v[34:35] op_sel_hi:[1, 0, 1]
	v_pk_fma_f32 v[76:77], v[166:167], v[60:61], v[30:31] op_sel_hi:[1, 0, 1]
	v_pk_fma_f32 v[84:85], v[166:167], v[74:75], v[26:27] op_sel_hi:[1, 0, 1]
	v_pk_fma_f32 v[92:93], v[166:167], v[78:79], v[22:23] op_sel_hi:[1, 0, 1]
	v_pk_fma_f32 v[96:97], v[166:167], v[82:83], v[18:19] op_sel_hi:[1, 0, 1]
	v_pk_fma_f32 v[100:101], v[166:167], v[86:87], v[14:15] op_sel_hi:[1, 0, 1]
	v_pk_fma_f32 v[104:105], v[166:167], v[90:91], v[6:7] op_sel_hi:[1, 0, 1]
	v_mov_b32_e32 v4, v39
	v_mov_b32_e32 v6, v87
	s_waitcnt vmcnt(0)
	v_pk_fma_f32 v[32:33], v[168:169], v[4:5], v[8:9] op_sel_hi:[1, 0, 1]
	v_pk_fma_f32 v[34:35], v[170:171], v[4:5], v[10:11] op_sel_hi:[1, 0, 1]
	v_mov_b32_e32 v4, v47
	v_pk_fma_f32 v[28:29], v[168:169], v[4:5], v[36:37] op_sel_hi:[1, 0, 1]
	v_pk_fma_f32 v[30:31], v[170:171], v[4:5], v[40:41] op_sel_hi:[1, 0, 1]
	v_mov_b32_e32 v4, v43
	v_pk_fma_f32 v[24:25], v[168:169], v[4:5], v[44:45] op_sel_hi:[1, 0, 1]
	v_pk_fma_f32 v[26:27], v[170:171], v[4:5], v[58:59] op_sel_hi:[1, 0, 1]
	v_mov_b32_e32 v4, v61
	v_pk_fma_f32 v[20:21], v[168:169], v[4:5], v[72:73] op_sel_hi:[1, 0, 1]
	v_pk_fma_f32 v[22:23], v[170:171], v[4:5], v[76:77] op_sel_hi:[1, 0, 1]
	v_mov_b32_e32 v4, v75
	v_pk_fma_f32 v[16:17], v[168:169], v[4:5], v[80:81] op_sel_hi:[1, 0, 1]
	v_pk_fma_f32 v[18:19], v[170:171], v[4:5], v[84:85] op_sel_hi:[1, 0, 1]
	v_mov_b32_e32 v4, v79
	v_pk_fma_f32 v[12:13], v[168:169], v[4:5], v[88:89] op_sel_hi:[1, 0, 1]
	v_pk_fma_f32 v[14:15], v[170:171], v[4:5], v[92:93] op_sel_hi:[1, 0, 1]
	v_mov_b32_e32 v4, v83
	v_mov_b32_e32 v36, v91
	v_pk_fma_f32 v[8:9], v[168:169], v[4:5], v[94:95] op_sel_hi:[1, 0, 1]
	v_pk_fma_f32 v[10:11], v[170:171], v[4:5], v[96:97] op_sel_hi:[1, 0, 1]
	v_pk_fma_f32 v[4:5], v[168:169], v[6:7], v[98:99] op_sel_hi:[1, 0, 1]
	v_pk_fma_f32 v[6:7], v[170:171], v[6:7], v[100:101] op_sel_hi:[1, 0, 1]
	v_pk_fma_f32 v[0:1], v[168:169], v[36:37], v[102:103] op_sel_hi:[1, 0, 1]
	v_pk_fma_f32 v[2:3], v[170:171], v[36:37], v[104:105] op_sel_hi:[1, 0, 1]
	s_cbranch_scc0 .LBB0_77
	v_lshlrev_b32_e32 v37, 2, v70
	v_mul_u32_u24_e32 v38, 0x1200, v69
	v_mul_lo_u32 v36, v48, 48
	v_add3_u32 v37, v66, v37, v38
	v_sub_u32_e32 v36, v68, v36
	s_barrier
	ds_write_b128 v37, v[32:35]
	ds_write_b128 v37, v[28:31] offset:512
	ds_write_b128 v37, v[24:27] offset:1024
	ds_write_b128 v37, v[20:23] offset:1536
	ds_write_b128 v37, v[16:19] offset:2048
	ds_write_b128 v37, v[12:15] offset:2560
	ds_write_b128 v37, v[8:11] offset:3072
	ds_write_b128 v37, v[4:7] offset:3584
	ds_write_b128 v37, v[0:3] offset:4096
	v_lshrrev_b32_e32 v2, 7, v52
	v_lshlrev_b32_e32 v36, 7, v36
	v_mul_hi_u32_u24_e32 v3, 0x6000, v2
	v_mul_u32_u24_e32 v2, 0x6000, v2
	v_add_u32_e32 v0, v51, v36
	v_ashrrev_i32_e32 v37, 31, v36
	v_and_b32_e32 v5, 0x7f, v67
	v_mad_i64_i32 v[2:3], s[28:29], v48, s54, v[2:3]
	v_or_b32_e32 v0, v0, v5
	v_lshl_add_u64 v[2:3], v[36:37], 2, v[2:3]
	v_lshlrev_b32_e32 v5, 2, v5
	v_ashrrev_i32_e32 v1, 31, v0
	v_or_b32_e32 v2, v2, v5
	v_and_b32_e32 v6, 0x200, v50
	v_lshl_add_u64 v[0:1], v[0:1], 2, s[14:15]
	v_or_b32_e32 v4, 0xffffff00, v52
	v_lshl_add_u64 v[2:3], s[22:23], 0, v[2:3]
	v_add3_u32 v5, v66, v6, v5
	s_mov_b64 s[28:29], 0
	s_waitcnt lgkmcnt(0)
	s_barrier

.LBB0_1976:
	v_mov_b32_e32 v0, v184
	s_nop 0
	v_ashrrev_i32_e32 v0, 8, v0
	v_add_u32_e32 v0, s18, v0
	v_mul_hi_i32 v1, v0, s20
	v_lshrrev_b32_e32 v2, 31, v1
	v_ashrrev_i32_e32 v1, 9, v1
	v_add_u32_e32 v9, v1, v2
	v_mul_i32_i24_e32 v1, 0x840, v9
	v_sub_u32_e32 v0, v0, v1
	v_cmp_lt_i32_e32 vcc, s21, v0
	s_and_saveexec_b64 s[2:3], vcc
	s_xor_b64 s[2:3], exec, s[2:3]
	s_cbranch_execz .LBB0_1978
	v_mov_b32_e32 v5, v184
	v_mov_b32_e32 v28, v184
	v_mov_b64_e32 v[2:3], s[6:7]
	v_lshlrev_b32_e32 v1, 2, v28
	v_and_b32_e32 v30, 60, v1
	v_lshlrev_b32_e32 v1, 6, v0
	v_and_b32_e32 v31, 0x3c0, v1
	v_lshlrev_b32_e32 v0, 2, v0
	v_or_b32_e32 v1, v30, v31
	v_and_b32_e32 v0, 0x7fffffc0, v0
	v_mad_i64_i32 v[2:3], s[14:15], v9, s22, v[2:3]
	v_bfe_u32 v29, v28, 4, 4
	v_add_u32_e32 v4, 0xffffea00, v0
	v_lshlrev_b32_e32 v6, 2, v1
	v_lshl_add_u64 v[10:11], v[2:3], 0, v[6:7]
	v_or_b32_e32 v6, v29, v4
	v_lshlrev_b64 v[0:1], 12, v[6:7]
	v_or_b32_e32 v16, 16, v6
	v_mov_b32_e32 v17, v7
	v_lshl_add_u64 v[0:1], v[10:11], 0, v[0:1]
	v_lshlrev_b64 v[16:17], 12, v[16:17]
	v_or_b32_e32 v20, 32, v6
	v_mov_b32_e32 v21, v7
	v_or_b32_e32 v6, 48, v6
	s_barrier
	global_load_dwordx4 v[0:3], v[0:1], off nt
	v_lshl_add_u64 v[16:17], v[10:11], 0, v[16:17]
	v_lshlrev_b64 v[20:21], 12, v[20:21]
	v_lshlrev_b64 v[24:25], 12, v[6:7]
	global_load_dwordx4 v[16:19], v[16:17], off nt
	v_lshl_add_u64 v[20:21], v[10:11], 0, v[20:21]
	v_lshl_add_u64 v[10:11], v[10:11], 0, v[24:25]
	global_load_dwordx4 v[20:23], v[20:21], off nt
	v_lshlrev_b32_e32 v5, 6, v5
	global_load_dwordx4 v[24:27], v[10:11], off nt
	v_mul_hi_i32_i24_e32 v11, 0x580000, v9
	v_mul_i32_i24_e32 v10, 0x580000, v9
	v_lshl_add_u64 v[8:9], s[10:11], 0, v[10:11]
	v_and_b32_e32 v5, 0xffffc000, v5
	v_lshlrev_b32_e32 v6, 1, v29
	v_mul_u32_u24_e32 v10, 0x90, v30
	v_or3_b32 v6, v5, v10, v6
	s_waitcnt vmcnt(3)
	v_bfe_u32 v10, v0, 16, 1
	v_bfe_u32 v11, v1, 16, 1
	v_bfe_u32 v29, v2, 16, 1
	v_bfe_u32 v30, v3, 16, 1
	v_add3_u32 v0, v0, v10, s24
	s_waitcnt vmcnt(2)
	v_bfe_u32 v10, v16, 16, 1
	v_add3_u32 v1, v1, v11, s24
	v_add3_u32 v2, v2, v29, s24
	v_add3_u32 v3, v3, v30, s24
	v_bfe_u32 v11, v17, 16, 1
	v_bfe_u32 v29, v18, 16, 1
	v_bfe_u32 v30, v19, 16, 1
	s_waitcnt vmcnt(1)
	v_bfe_u32 v32, v20, 16, 1
	v_bfe_u32 v33, v21, 16, 1
	v_bfe_u32 v34, v22, 16, 1
	v_bfe_u32 v35, v23, 16, 1
	s_waitcnt vmcnt(0)
	v_bfe_u32 v36, v24, 16, 1
	v_bfe_u32 v37, v25, 16, 1
	v_bfe_u32 v38, v26, 16, 1
	v_bfe_u32 v39, v27, 16, 1
	ds_write_b16_d16_hi v6, v0
	ds_write_b16_d16_hi v6, v1 offset:144
	ds_write_b16_d16_hi v6, v2 offset:288
	ds_write_b16_d16_hi v6, v3 offset:432
	v_add3_u32 v0, v16, v10, s24
	v_add3_u32 v1, v17, v11, s24
	v_add3_u32 v2, v18, v29, s24
	v_add3_u32 v3, v19, v30, s24
	v_add3_u32 v10, v20, v32, s24
	v_add3_u32 v11, v21, v33, s24
	v_add3_u32 v16, v22, v34, s24
	v_add3_u32 v17, v23, v35, s24
	v_add3_u32 v18, v24, v36, s24
	v_add3_u32 v19, v25, v37, s24
	v_add3_u32 v20, v26, v38, s24
	ds_write_b16_d16_hi v6, v0 offset:32
	ds_write_b16_d16_hi v6, v1 offset:176
	ds_write_b16_d16_hi v6, v2 offset:320
	ds_write_b16_d16_hi v6, v3 offset:464
	ds_write_b16_d16_hi v6, v10 offset:64
	ds_write_b16_d16_hi v6, v11 offset:208
	ds_write_b16_d16_hi v6, v16 offset:352
	ds_write_b16_d16_hi v6, v17 offset:496
	ds_write_b16_d16_hi v6, v18 offset:96
	ds_write_b16_d16_hi v6, v19 offset:240
	ds_write_b16_d16_hi v6, v20 offset:384
	v_add3_u32 v0, v27, v39, s24
	ds_write_b16_d16_hi v6, v0 offset:528
	v_lshlrev_b32_e32 v0, 4, v28
	v_and_b32_e32 v6, 0x70, v0
	v_bfe_u32 v2, v28, 3, 5
	v_or_b32_e32 v3, v5, v6
	v_mov_b32_e32 v5, v7
	v_lshl_add_u64 v[0:1], v[4:5], 1, v[8:9]
	v_mad_u32_u24 v8, v2, s23, v3
	s_waitcnt lgkmcnt(0)
	s_barrier
	v_lshl_add_u64 v[4:5], v[0:1], 0, v[6:7]
	v_or_b32_e32 v18, v2, v31
	ds_read_b128 v[0:3], v8
	v_mul_u32_u24_e32 v6, 0xb00, v18
	v_lshlrev_b32_e32 v6, 1, v6
	v_lshl_add_u64 v[16:17], v[4:5], 0, v[6:7]
	ds_read_b128 v[8:11], v8 offset:4608
	s_waitcnt lgkmcnt(1)
	global_store_dwordx4 v[16:17], v[0:3], off
	s_nop 1
	v_or_b32_e32 v0, 32, v18
	v_mul_u32_u24_e32 v0, 0xb00, v0
	v_lshlrev_b32_e32 v6, 1, v0
	v_lshl_add_u64 v[0:1], v[4:5], 0, v[6:7]
	s_waitcnt lgkmcnt(0)
	global_store_dwordx4 v[0:1], v[8:11], off
.LBB0_1978:
	s_andn2_saveexec_b64 s[14:15], s[2:3]
	s_cbranch_execz .LBB0_1975
	v_mul_i32_i24_e32 v1, 0xba3, v0
	v_lshrrev_b32_e32 v2, 31, v1
	v_ashrrev_i32_e32 v1, 18, v1
	v_add_u16_e32 v5, v1, v2
	v_mul_lo_u16_e32 v1, 0x58, v5
	v_sub_u16_e32 v17, v0, v1
	v_mov_b64_e32 v[0:1], s[4:5]
	v_mad_i64_i32 v[2:3], s[2:3], v9, s25, v[0:1]
	v_mov_b32_e32 v1, v184
	v_mov_b32_e32 v6, v184
	v_lshlrev_b32_sdwa v16, v12, sext(v17) dst_sel:DWORD dst_unused:UNUSED_PAD src0_sel:DWORD src1_sel:WORD_0
	v_lshlrev_b32_e32 v0, 2, v6
	v_and_b32_e32 v20, 60, v0
	v_or_b32_e32 v4, v20, v16
	v_lshlrev_b32_sdwa v8, v12, sext(v5) dst_sel:DWORD dst_unused:UNUSED_PAD src0_sel:DWORD src1_sel:WORD_0
	v_ashrrev_i32_e32 v5, 31, v4
	v_bfe_u32 v19, v6, 4, 4
	v_cmp_gt_i32_e32 vcc, s26, v4
	v_lshl_add_u64 v[10:11], v[4:5], 2, v[2:3]
	v_mov_b32_e32 v0, 0
	v_mov_b32_e32 v2, 0
	v_mov_b32_e32 v3, 0
	v_mov_b32_e32 v4, 0
	v_mov_b32_e32 v5, 0
	s_barrier
	s_and_saveexec_b64 s[2:3], vcc
	s_cbranch_execz .LBB0_1981
	v_or_b32_e32 v2, v19, v8
	v_mul_i32_i24_e32 v2, 0x1600, v2
	v_ashrrev_i32_e32 v3, 31, v2
	v_lshl_add_u64 v[2:3], v[2:3], 2, v[10:11]
	global_load_dwordx4 v[2:5], v[2:3], off nt
.LBB0_1981:
	s_or_b64 exec, exec, s[2:3]
	v_lshlrev_b32_e32 v1, 6, v1
	v_and_b32_e32 v18, 0xffffc000, v1
	v_mul_u32_u24_e32 v1, 0x90, v20
	v_or_b32_e32 v1, v18, v1
	s_waitcnt vmcnt(0)
	v_bfe_u32 v20, v2, 16, 1
	v_add3_u32 v2, v2, v20, s24
	v_lshl_add_u32 v20, v19, 1, v1
	v_bfe_u32 v1, v3, 16, 1
	v_add3_u32 v1, v3, v1, s24
	ds_write_b16_d16_hi v20, v1 offset:144
	v_bfe_u32 v1, v4, 16, 1
	v_add3_u32 v1, v4, v1, s24
	ds_write_b16_d16_hi v20, v1 offset:288
	v_bfe_u32 v1, v5, 16, 1
	v_add3_u32 v1, v5, v1, s24
	ds_write_b16_d16_hi v20, v2
	ds_write_b16_d16_hi v20, v1 offset:432
	v_mov_b32_e32 v1, 0
	v_mov_b32_e32 v2, 0
	v_mov_b32_e32 v3, 0
	s_and_saveexec_b64 s[2:3], vcc
	s_cbranch_execz .LBB0_1983
	v_or3_b32 v0, v19, v8, 16
	v_mul_i32_i24_e32 v0, 0x1600, v0
	v_ashrrev_i32_e32 v1, 31, v0
	v_lshl_add_u64 v[0:1], v[0:1], 2, v[10:11]
	global_load_dwordx4 v[0:3], v[0:1], off nt
.LBB0_1983:
	s_or_b64 exec, exec, s[2:3]
	s_waitcnt vmcnt(0)
	v_bfe_u32 v4, v0, 16, 1
	v_add3_u32 v0, v0, v4, s24
	ds_write_b16_d16_hi v20, v0 offset:32
	v_bfe_u32 v0, v1, 16, 1
	v_add3_u32 v0, v1, v0, s24
	ds_write_b16_d16_hi v20, v0 offset:176
	v_bfe_u32 v0, v2, 16, 1
	v_add3_u32 v0, v2, v0, s24
	ds_write_b16_d16_hi v20, v0 offset:320
	v_bfe_u32 v0, v3, 16, 1
	v_add3_u32 v0, v3, v0, s24
	ds_write_b16_d16_hi v20, v0 offset:464
	v_mov_b32_e32 v0, 0
	v_mov_b32_e32 v2, 0
	v_mov_b32_e32 v3, 0
	v_mov_b32_e32 v4, 0
	v_mov_b32_e32 v5, 0
	s_and_saveexec_b64 s[2:3], vcc
	s_cbranch_execz .LBB0_1985
	v_or3_b32 v1, v19, v8, 32
	v_mul_i32_i24_e32 v2, 0x1600, v1
	v_ashrrev_i32_e32 v3, 31, v2
	v_lshl_add_u64 v[2:3], v[2:3], 2, v[10:11]
	global_load_dwordx4 v[2:5], v[2:3], off nt
.LBB0_1985:
	s_or_b64 exec, exec, s[2:3]
	s_waitcnt vmcnt(0)
	v_bfe_u32 v1, v2, 16, 1
	v_add3_u32 v1, v2, v1, s24
	ds_write_b16_d16_hi v20, v1 offset:64
	v_bfe_u32 v1, v3, 16, 1
	v_add3_u32 v1, v3, v1, s24
	ds_write_b16_d16_hi v20, v1 offset:208
	v_bfe_u32 v1, v4, 16, 1
	v_add3_u32 v1, v4, v1, s24
	ds_write_b16_d16_hi v20, v1 offset:352
	v_bfe_u32 v1, v5, 16, 1
	v_add3_u32 v1, v5, v1, s24
	ds_write_b16_d16_hi v20, v1 offset:496
	v_mov_b32_e32 v1, 0
	v_mov_b32_e32 v2, 0
	v_mov_b32_e32 v3, 0
	s_and_saveexec_b64 s[2:3], vcc
	s_cbranch_execz .LBB0_1987
	v_or3_b32 v0, v19, v8, 48
	v_mul_i32_i24_e32 v0, 0x1600, v0
	v_ashrrev_i32_e32 v1, 31, v0
	v_lshl_add_u64 v[0:1], v[0:1], 2, v[10:11]
	global_load_dwordx4 v[0:3], v[0:1], off nt

.LBB0_2321:
	s_or_b64 exec, exec, s[4:5]
	s_waitcnt lgkmcnt(0)
	s_barrier
	ds_read_b32 v0, v189
	s_mov_b64 s[4:5], -1
	s_waitcnt lgkmcnt(0)
	v_cmp_lt_i32_e32 vcc, s48, v0
	s_cbranch_vccnz .LBB0_2316
	v_mov_b32_e32 v1, v184
	v_lshlrev_b32_e32 v0, 1, v0
	v_add_u32_e32 v0, 0x580, v0
	v_ashrrev_i32_e32 v1, 8, v1
	v_add_u32_e32 v0, v0, v1
	s_mov_b32 s4, 0x3e0f83e1
	v_mul_hi_i32 v1, v0, s4
	v_lshrrev_b32_e32 v2, 31, v1
	v_ashrrev_i32_e32 v1, 9, v1
	v_add_u32_e32 v7, v1, v2
	v_mul_i32_i24_e32 v1, 0x840, v7
	v_sub_u32_e32 v0, v0, v1
	v_cmp_lt_i32_e32 vcc, s48, v0
	s_and_saveexec_b64 s[4:5], vcc
	s_xor_b64 s[4:5], exec, s[4:5]
	s_cbranch_execz .LBB0_2324
	v_mov_b32_e32 v1, v184
	v_mov_b32_e32 v22, v184
	v_mov_b64_e32 v[2:3], s[14:15]
	v_lshlrev_b32_e32 v4, 2, v22
	v_and_b32_e32 v24, 60, v4
	v_lshlrev_b32_e32 v4, 6, v0
	v_and_b32_e32 v25, 0x3c0, v4
	v_lshlrev_b32_e32 v0, 2, v0
	v_or_b32_e32 v4, v24, v25
	v_and_b32_e32 v0, 0x7fffffc0, v0
	v_mad_i64_i32 v[2:3], s[22:23], v7, s47, v[2:3]
	v_bfe_u32 v23, v22, 4, 4
	v_add_u32_e32 v0, 0xffffea00, v0
	v_lshlrev_b32_e32 v134, 2, v4
	v_lshl_add_u64 v[16:17], v[2:3], 0, v[134:135]
	v_or_b32_e32 v134, v23, v0
	v_lshlrev_b64 v[2:3], 12, v[134:135]
	v_or_b32_e32 v8, 16, v134
	v_mov_b32_e32 v9, v135
	v_lshl_add_u64 v[2:3], v[16:17], 0, v[2:3]
	v_lshlrev_b64 v[8:9], 12, v[8:9]
	v_or_b32_e32 v12, 32, v134
	v_mov_b32_e32 v13, v135
	v_or_b32_e32 v134, 48, v134
	s_barrier
	global_load_dwordx4 v[2:5], v[2:3], off nt
	v_lshl_add_u64 v[8:9], v[16:17], 0, v[8:9]
	v_lshlrev_b64 v[12:13], 12, v[12:13]
	v_lshlrev_b64 v[18:19], 12, v[134:135]
	global_load_dwordx4 v[8:11], v[8:9], off nt
	v_lshl_add_u64 v[12:13], v[16:17], 0, v[12:13]
	v_lshl_add_u64 v[16:17], v[16:17], 0, v[18:19]
	global_load_dwordx4 v[12:15], v[12:13], off nt
	v_mul_hi_i32_i24_e32 v21, 0x580000, v7
	global_load_dwordx4 v[16:19], v[16:17], off nt
	v_mul_i32_i24_e32 v20, 0x580000, v7
	v_lshlrev_b32_e32 v1, 6, v1
	v_lshl_add_u64 v[6:7], s[12:13], 0, v[20:21]
	v_and_b32_e32 v1, 0xffffc000, v1
	v_lshlrev_b32_e32 v20, 1, v23
	v_mul_u32_u24_e32 v21, 0x90, v24
	v_or3_b32 v20, v1, v21, v20
	s_waitcnt vmcnt(3)
	v_bfe_u32 v21, v2, 16, 1
	v_bfe_u32 v23, v3, 16, 1
	v_bfe_u32 v24, v4, 16, 1
	v_bfe_u32 v26, v5, 16, 1
	v_add3_u32 v2, v2, v21, s46
	v_add3_u32 v3, v3, v23, s46
	s_waitcnt vmcnt(2)
	v_bfe_u32 v21, v8, 16, 1
	v_bfe_u32 v23, v9, 16, 1
	v_add3_u32 v4, v4, v24, s46
	v_add3_u32 v5, v5, v26, s46
	v_bfe_u32 v24, v10, 16, 1
	v_bfe_u32 v26, v11, 16, 1
	s_waitcnt vmcnt(1)
	v_bfe_u32 v27, v12, 16, 1
	v_bfe_u32 v28, v13, 16, 1
	v_bfe_u32 v29, v14, 16, 1
	v_bfe_u32 v30, v15, 16, 1
	s_waitcnt vmcnt(0)
	v_bfe_u32 v31, v16, 16, 1
	v_bfe_u32 v32, v17, 16, 1
	v_bfe_u32 v33, v18, 16, 1
	ds_write_b16_d16_hi v20, v2
	ds_write_b16_d16_hi v20, v3 offset:144
	ds_write_b16_d16_hi v20, v4 offset:288
	ds_write_b16_d16_hi v20, v5 offset:432
	v_add3_u32 v2, v8, v21, s46
	v_add3_u32 v3, v9, v23, s46
	v_bfe_u32 v34, v19, 16, 1
	v_add3_u32 v4, v10, v24, s46
	v_add3_u32 v5, v11, v26, s46
	v_add3_u32 v8, v12, v27, s46
	v_add3_u32 v9, v13, v28, s46
	v_add3_u32 v10, v14, v29, s46
	v_add3_u32 v11, v15, v30, s46
	v_add3_u32 v12, v16, v31, s46
	v_add3_u32 v13, v17, v32, s46
	v_add3_u32 v14, v18, v33, s46
	ds_write_b16_d16_hi v20, v2 offset:32
	ds_write_b16_d16_hi v20, v3 offset:176
	ds_write_b16_d16_hi v20, v4 offset:320
	ds_write_b16_d16_hi v20, v5 offset:464
	ds_write_b16_d16_hi v20, v8 offset:64
	ds_write_b16_d16_hi v20, v9 offset:208
	ds_write_b16_d16_hi v20, v10 offset:352
	ds_write_b16_d16_hi v20, v11 offset:496
	ds_write_b16_d16_hi v20, v12 offset:96
	ds_write_b16_d16_hi v20, v13 offset:240
	ds_write_b16_d16_hi v20, v14 offset:384
	v_lshlrev_b32_e32 v3, 4, v22
	v_add3_u32 v2, v19, v34, s46
	v_and_b32_e32 v134, 0x70, v3
	ds_write_b16_d16_hi v20, v2 offset:528
	v_bfe_u32 v2, v22, 3, 5
	v_or_b32_e32 v3, v1, v134
	v_mov_b32_e32 v1, v135
	v_lshl_add_u64 v[0:1], v[0:1], 1, v[6:7]
	v_mad_u32_u24 v4, v2, s49, v3
	s_waitcnt lgkmcnt(0)
	s_barrier
	v_lshl_add_u64 v[8:9], v[0:1], 0, v[134:135]
	v_or_b32_e32 v12, v2, v25
	ds_read_b128 v[0:3], v4
	v_mul_u32_u24_e32 v5, 0xb00, v12
	v_lshlrev_b32_e32 v134, 1, v5
	v_lshl_add_u64 v[10:11], v[8:9], 0, v[134:135]
	ds_read_b128 v[4:7], v4 offset:4608
	s_waitcnt lgkmcnt(1)
	global_store_dwordx4 v[10:11], v[0:3], off
	s_nop 1
	v_or_b32_e32 v0, 32, v12
	v_mul_u32_u24_e32 v0, 0xb00, v0
	v_lshlrev_b32_e32 v134, 1, v0
	v_lshl_add_u64 v[0:1], v[8:9], 0, v[134:135]
	s_waitcnt lgkmcnt(0)
	global_store_dwordx4 v[0:1], v[4:7], off
.LBB0_2324:
	s_andn2_saveexec_b64 s[22:23], s[4:5]
	s_cbranch_execz .LBB0_2315
	v_mul_i32_i24_e32 v1, 0xba3, v0
	v_lshrrev_b32_e32 v2, 31, v1
	v_ashrrev_i32_e32 v1, 18, v1
	v_add_u16_e32 v5, v1, v2
	v_mul_lo_u16_e32 v1, 0x58, v5
	v_sub_u16_e32 v12, v0, v1
	v_mov_b64_e32 v[0:1], s[8:9]
	s_mov_b32 s4, 0x1600000
	v_mad_i64_i32 v[2:3], s[4:5], v7, s4, v[0:1]
	v_mov_b32_e32 v1, v184
	v_mov_b32_e32 v11, v184
	v_lshlrev_b32_sdwa v10, v193, sext(v12) dst_sel:DWORD dst_unused:UNUSED_PAD src0_sel:DWORD src1_sel:WORD_0
	v_lshlrev_b32_e32 v0, 2, v11
	v_and_b32_e32 v15, 60, v0
	v_or_b32_e32 v4, v15, v10
	v_lshlrev_b32_sdwa v6, v193, sext(v5) dst_sel:DWORD dst_unused:UNUSED_PAD src0_sel:DWORD src1_sel:WORD_0
	v_ashrrev_i32_e32 v5, 31, v4
	v_bfe_u32 v14, v11, 4, 4
	v_cmp_gt_i32_e32 vcc, s35, v4
	v_lshl_add_u64 v[8:9], v[4:5], 2, v[2:3]
	v_mov_b32_e32 v0, 0
	v_mov_b32_e32 v2, 0
	v_mov_b32_e32 v3, 0
	v_mov_b32_e32 v4, 0
	v_mov_b32_e32 v5, 0
	s_barrier
	s_and_saveexec_b64 s[4:5], vcc
	s_cbranch_execz .LBB0_2327
	v_or_b32_e32 v2, v14, v6
	v_mul_i32_i24_e32 v2, 0x1600, v2
	v_ashrrev_i32_e32 v3, 31, v2
	v_lshl_add_u64 v[2:3], v[2:3], 2, v[8:9]
	global_load_dwordx4 v[2:5], v[2:3], off nt
.LBB0_2327:
	s_or_b64 exec, exec, s[4:5]
	v_lshlrev_b32_e32 v1, 6, v1
	v_and_b32_e32 v13, 0xffffc000, v1
	v_mul_u32_u24_e32 v1, 0x90, v15
	v_or_b32_e32 v1, v13, v1
	s_waitcnt vmcnt(0)
	v_bfe_u32 v15, v2, 16, 1
	v_add3_u32 v2, v2, v15, s46
	v_lshl_add_u32 v15, v14, 1, v1
	v_bfe_u32 v1, v3, 16, 1
	v_add3_u32 v1, v3, v1, s46
	ds_write_b16_d16_hi v15, v1 offset:144
	v_bfe_u32 v1, v4, 16, 1
	v_add3_u32 v1, v4, v1, s46
	ds_write_b16_d16_hi v15, v1 offset:288
	v_bfe_u32 v1, v5, 16, 1
	v_add3_u32 v1, v5, v1, s46
	ds_write_b16_d16_hi v15, v2
	ds_write_b16_d16_hi v15, v1 offset:432
	v_mov_b32_e32 v1, 0
	v_mov_b32_e32 v2, 0
	v_mov_b32_e32 v3, 0
	s_and_saveexec_b64 s[4:5], vcc
	s_cbranch_execz .LBB0_2329
	v_or3_b32 v0, v14, v6, 16
	v_mul_i32_i24_e32 v0, 0x1600, v0
	v_ashrrev_i32_e32 v1, 31, v0
	v_lshl_add_u64 v[0:1], v[0:1], 2, v[8:9]
	global_load_dwordx4 v[0:3], v[0:1], off nt
.LBB0_2329:
	s_or_b64 exec, exec, s[4:5]
	s_waitcnt vmcnt(0)
	v_bfe_u32 v4, v0, 16, 1
	v_add3_u32 v0, v0, v4, s46
	ds_write_b16_d16_hi v15, v0 offset:32
	v_bfe_u32 v0, v1, 16, 1
	v_add3_u32 v0, v1, v0, s46
	ds_write_b16_d16_hi v15, v0 offset:176
	v_bfe_u32 v0, v2, 16, 1
	v_add3_u32 v0, v2, v0, s46
	ds_write_b16_d16_hi v15, v0 offset:320
	v_bfe_u32 v0, v3, 16, 1
	v_add3_u32 v0, v3, v0, s46
	ds_write_b16_d16_hi v15, v0 offset:464
	v_mov_b32_e32 v0, 0
	v_mov_b32_e32 v2, 0
	v_mov_b32_e32 v3, 0
	v_mov_b32_e32 v4, 0
	v_mov_b32_e32 v5, 0
	s_and_saveexec_b64 s[4:5], vcc
	s_cbranch_execz .LBB0_2331
	v_or3_b32 v1, v14, v6, 32
	v_mul_i32_i24_e32 v2, 0x1600, v1
	v_ashrrev_i32_e32 v3, 31, v2
	v_lshl_add_u64 v[2:3], v[2:3], 2, v[8:9]
	global_load_dwordx4 v[2:5], v[2:3], off nt
.LBB0_2331:
	s_or_b64 exec, exec, s[4:5]
	s_waitcnt vmcnt(0)
	v_bfe_u32 v1, v2, 16, 1
	v_add3_u32 v1, v2, v1, s46
	ds_write_b16_d16_hi v15, v1 offset:64
	v_bfe_u32 v1, v3, 16, 1
	v_add3_u32 v1, v3, v1, s46
	ds_write_b16_d16_hi v15, v1 offset:208
	v_bfe_u32 v1, v4, 16, 1
	v_add3_u32 v1, v4, v1, s46
	ds_write_b16_d16_hi v15, v1 offset:352
	v_bfe_u32 v1, v5, 16, 1
	v_add3_u32 v1, v5, v1, s46
	ds_write_b16_d16_hi v15, v1 offset:496
	v_mov_b32_e32 v1, 0
	v_mov_b32_e32 v2, 0
	v_mov_b32_e32 v3, 0
	s_and_saveexec_b64 s[4:5], vcc
	s_cbranch_execz .LBB0_2333
	v_or3_b32 v0, v14, v6, 48
	v_mul_i32_i24_e32 v0, 0x1600, v0
	v_ashrrev_i32_e32 v1, 31, v0
	v_lshl_add_u64 v[0:1], v[0:1], 2, v[8:9]
	global_load_dwordx4 v[0:3], v[0:1], off nt
